# first-barrier census: the sixteen XCC counter loads issued back to back with one wait (was one round trip per counter)
# baseline (speedup 1.0000x reference)
; __device__ __forceinline__ unsigned xb_ld(unsigned* p)              { return __hip_atomic_load(p, __ATOMIC_RELAXED, __HIP_MEMORY_SCOPE_AGENT); }
; __device__ __forceinline__ void xcd_barrier_complete(unsigned* bar, unsigned x, unsigned& nloc, unsigned& nx) {
;     ...
;     for (;;) {
;         sum = 0u; cnt = 0u; mine = 0u;
; #pragma unroll
;         for (unsigned j = 0; j < 16; ++j) { const unsigned c = xb_ld(&bar[XB_XCNT(j)]); sum += c; cnt += (c > 0u) ? 1u : 0u; mine = (j == x) ? c : mine; }
;         if (sum == G) break;
;         __builtin_amdgcn_s_sleep(1);
;         if ((++sp & 255u) == 0u) { if (xb_ld(&bar[XB_TMO])) break; if (sp > XB_SPIN_CAP) { atomicAdd(&bar[XB_TMO], 1u); break; } }
;     }
.LBB0_1013:
	global_load_dword v4, v1, s[18:19] sc1
	global_load_dword v0, v1, s[84:85] sc1
	global_load_dword v2, v1, s[86:87] sc1
	global_load_dword v3, v1, s[48:49] sc1
	s_mov_b64 s[4:5], -1
	v_readlane_b32 s2, v251, 9
	v_readlane_b32 s3, v251, 10
	s_nop 4
	global_load_dword v5, v1, s[2:3] sc1
	v_readlane_b32 s2, v251, 11
	v_readlane_b32 s3, v251, 12
	s_nop 4
	global_load_dword v6, v1, s[2:3] sc1
	v_readlane_b32 s2, v251, 13
	v_readlane_b32 s3, v251, 14
	s_nop 4
	global_load_dword v7, v1, s[2:3] sc1
	v_readlane_b32 s2, v251, 15
	v_readlane_b32 s3, v251, 16
	s_nop 4
	global_load_dword v8, v1, s[2:3] sc1
	v_readlane_b32 s2, v251, 17
	v_readlane_b32 s3, v251, 18
	s_nop 4
	global_load_dword v9, v1, s[2:3] sc1
	v_readlane_b32 s2, v251, 19
	v_readlane_b32 s3, v251, 20
	s_nop 4
	global_load_dword v10, v1, s[2:3] sc1
	v_readlane_b32 s2, v251, 21
	v_readlane_b32 s3, v251, 22
	s_nop 4
	global_load_dword v11, v1, s[2:3] sc1
	v_readlane_b32 s2, v251, 23
	v_readlane_b32 s3, v251, 24
	s_nop 4
	global_load_dword v12, v1, s[2:3] sc1
	v_readlane_b32 s2, v251, 25
	v_readlane_b32 s3, v251, 26
	s_nop 4
	global_load_dword v13, v1, s[2:3] sc1
	v_readlane_b32 s2, v251, 27
	v_readlane_b32 s3, v251, 28
	s_nop 4
	global_load_dword v14, v1, s[2:3] sc1
	v_readlane_b32 s2, v251, 29
	v_readlane_b32 s3, v251, 30
	s_nop 4
	global_load_dword v15, v1, s[2:3] sc1
	v_readlane_b32 s2, v251, 31
	v_readlane_b32 s3, v251, 32
	s_nop 4
	global_load_dword v16, v1, s[2:3] sc1
	s_mov_b64 s[2:3], -1
	s_waitcnt vmcnt(0)
	v_add_u32_e32 v17, v0, v4
	v_add_u32_e32 v17, v17, v2
	v_add_u32_e32 v17, v17, v3
	v_add_u32_e32 v17, v17, v5
	v_add_u32_e32 v17, v17, v6
	v_add_u32_e32 v17, v17, v7
	v_add_u32_e32 v17, v17, v8
	v_add_u32_e32 v17, v17, v9
	v_add_u32_e32 v17, v17, v10
	v_add_u32_e32 v17, v17, v11
	v_add_u32_e32 v17, v17, v12
	v_add_u32_e32 v17, v17, v13
	v_add_u32_e32 v17, v17, v14
	v_add_u32_e32 v17, v17, v15
	v_add_u32_e32 v17, v17, v16
	v_cmp_eq_u32_e32 vcc, s8, v17
	s_cbranch_vccnz .LBB0_1012
	s_and_b32 s2, s9, 0xff
	s_cmp_eq_u32 s2, 0
	s_mov_b64 s[2:3], -1
	s_mov_b64 s[6:7], -1
	s_sleep 1
	s_cbranch_scc1 .LBB0_1017
	s_and_b64 vcc, exec, s[6:7]
	s_cbranch_vccz .LBB0_1012
